# indexer loop rewrite + select row prefetch + P0 k-scale loads hoisted (all 16 streaming loads of a conversion item in flight)
# speedup vs baseline: 1.0073x; 1.0003x over previous
; DI void tr_item(const TrSrc& s, bf16* WT, int dK, int n0, int k0, LAS unsigned* T, int lane) {
;     ...
;     for (int st = 0; st < 8; ++st) { const int k = k0 + 8 * st + 2 * kq;
; #pragma unroll
;         for (int j = 0; j < 2; ++j) v[st][j] = (nok && k + j < s.kvalid) ? __builtin_nontemporal_load((const f32x4*)(s.p + (size_t)(k + j) * s.ld + s.col0 + 4 * ng)) : (f32x4){0.f, 0.f, 0.f, 0.f};
;         f32x2 c = {1.f, 1.f};
;         if (s.ksc) c = *(const f32x2*)(s.ksc + k);
;         if (s.mumode == 1) { const f32x2 m = *(const f32x2*)(s.mu + k); c = c * (1.0f - m); } else if (s.mumode == 2) { const f32x2 m = *(const f32x2*)(s.mu + k); c = c * m; }
;         sc[st] = c; }
.LBB0_68:
	s_lshl_b32 s24, s7, 6
	s_ashr_i32 s7, s6, 31
	s_lshl_b64 s[6:7], s[6:7], 2
	v_add_u32_e32 v78, s24, v122
	s_add_u32 s6, s28, s6
	v_cmp_gt_u32_e64 s[4:5], s61, v66
	s_addc_u32 s7, s29, s7
	v_cmp_gt_i32_e32 vcc, s41, v78
	v_lshl_add_u64 v[80:81], s[6:7], 0, v[68:69]
	s_and_b64 s[28:29], s[4:5], vcc
	s_and_b64 vcc, exec, s[20:21]
	s_cbranch_vccz .Lp0_nohoist
	s_cmp_lg_u32 s25, 0
	s_cbranch_scc1 .Lp0_nohoist
	v_ashrrev_i32_e32 v79, 31, v78
	v_lshl_add_u64 v[96:97], v[78:79], 2, s[14:15]
	global_load_dwordx2 v[82:83], v[96:97], off
	global_load_dwordx2 v[84:85], v[96:97], off offset:32
	global_load_dwordx2 v[86:87], v[96:97], off offset:64
	global_load_dwordx2 v[88:89], v[96:97], off offset:96
	global_load_dwordx2 v[90:91], v[96:97], off offset:128
	global_load_dwordx2 v[92:93], v[96:97], off offset:160
	global_load_dwordx2 v[94:95], v[96:97], off offset:192
.Lp0_nohoist:
	v_mov_b32_e32 v4, 0
	v_mov_b32_e32 v0, 0
	v_mov_b32_e32 v1, 0
	v_mov_b32_e32 v2, 0
	v_mov_b32_e32 v3, 0
	s_and_saveexec_b64 s[6:7], s[28:29]
	s_cbranch_execz .LBB0_70
	v_ashrrev_i32_e32 v0, 31, v78
	v_mul_lo_u32 v2, s27, v78
	v_mul_lo_u32 v3, s26, v0
	v_mad_u64_u32 v[0:1], s[28:29], s26, v78, 0
	v_add3_u32 v1, v1, v3, v2
	v_lshl_add_u64 v[0:1], v[0:1], 2, v[80:81]
	global_load_dwordx4 v[0:3], v[0:1], off nt

; DI void tr_item(const TrSrc& s, bf16* WT, int dK, int n0, int k0, LAS unsigned* T, int lane) {
;     ...
;     for (int st = 0; st < 8; ++st) { const int k = k0 + 8 * st + 2 * kq;
; #pragma unroll
;         for (int j = 0; j < 2; ++j) v[st][j] = (nok && k + j < s.kvalid) ? __builtin_nontemporal_load((const f32x4*)(s.p + (size_t)(k + j) * s.ld + s.col0 + 4 * ng)) : (f32x4){0.f, 0.f, 0.f, 0.f};
;         f32x2 c = {1.f, 1.f};
;         if (s.ksc) c = *(const f32x2*)(s.ksc + k);
;         if (s.mumode == 1) { const f32x2 m = *(const f32x2*)(s.mu + k); c = c * (1.0f - m); } else if (s.mumode == 2) { const f32x2 m = *(const f32x2*)(s.mu + k); c = c * m; }
;         sc[st] = c; }
.LBB0_74:
	s_or_b64 exec, exec, s[6:7]
	v_cndmask_b32_e64 v8, 0, 1, s[20:21]
	v_cmp_ne_u32_e64 s[6:7], 1, v8
	s_andn2_b64 vcc, exec, s[20:21]
	s_cbranch_vccnz .LBB0_157
	s_cmp_eq_u32 s25, 0
	s_cbranch_scc1 .Lp0_join_0
	v_ashrrev_i32_e32 v79, 31, v78
	v_lshl_add_u64 v[8:9], v[78:79], 2, s[14:15]
	global_load_dwordx2 v[8:9], v[8:9], off
	s_cmp_gt_i32 s25, 1
	s_mov_b64 s[28:29], -1
	s_cbranch_scc0 .LBB0_77

; DI void tr_item(const TrSrc& s, bf16* WT, int dK, int n0, int k0, LAS unsigned* T, int lane) {
;     ...
;     for (int st = 0; st < 8; ++st) { const int k = k0 + 8 * st + 2 * kq;
; #pragma unroll
;         for (int j = 0; j < 2; ++j) v[st][j] = (nok && k + j < s.kvalid) ? __builtin_nontemporal_load((const f32x4*)(s.p + (size_t)(k + j) * s.ld + s.col0 + 4 * ng)) : (f32x4){0.f, 0.f, 0.f, 0.f};
;         f32x2 c = {1.f, 1.f};
;         if (s.ksc) c = *(const f32x2*)(s.ksc + k);
;         if (s.mumode == 1) { const f32x2 m = *(const f32x2*)(s.mu + k); c = c * (1.0f - m); } else if (s.mumode == 2) { const f32x2 m = *(const f32x2*)(s.mu + k); c = c * m; }
;         sc[st] = c; }
.LBB0_80:
	s_waitcnt vmcnt(0)
	v_mov_b64_e32 v[82:83], v[8:9]
.LBB0_81:
	s_waitcnt vmcnt(0)
.Lp0_join_0:
	v_cmp_gt_i32_e32 vcc, s42, v78
	s_and_b64 s[58:59], s[4:5], vcc
	v_mov_b32_e32 v8, 0
	v_mov_b32_e32 v12, 0
	v_mov_b32_e32 v13, 0
	v_mov_b32_e32 v14, 0
	v_mov_b32_e32 v15, 0
	s_and_saveexec_b64 s[28:29], s[58:59]
	s_cbranch_execz .LBB0_83
	v_add_u32_e32 v9, 8, v78
	v_ashrrev_i32_e32 v10, 31, v9
	v_mul_lo_u32 v12, s26, v10
	v_mul_lo_u32 v13, s27, v9
	v_mad_u64_u32 v[10:11], s[58:59], s26, v9, 0
	v_add3_u32 v11, v11, v12, v13
	v_lshl_add_u64 v[10:11], v[10:11], 2, v[80:81]
	global_load_dwordx4 v[12:15], v[10:11], off nt

; DI void tr_item(const TrSrc& s, bf16* WT, int dK, int n0, int k0, LAS unsigned* T, int lane) {
;     ...
;     for (int st = 0; st < 8; ++st) { const int k = k0 + 8 * st + 2 * kq;
; #pragma unroll
;         for (int j = 0; j < 2; ++j) v[st][j] = (nok && k + j < s.kvalid) ? __builtin_nontemporal_load((const f32x4*)(s.p + (size_t)(k + j) * s.ld + s.col0 + 4 * ng)) : (f32x4){0.f, 0.f, 0.f, 0.f};
;         f32x2 c = {1.f, 1.f};
;         if (s.ksc) c = *(const f32x2*)(s.ksc + k);
;         if (s.mumode == 1) { const f32x2 m = *(const f32x2*)(s.mu + k); c = c * (1.0f - m); } else if (s.mumode == 2) { const f32x2 m = *(const f32x2*)(s.mu + k); c = c * m; }
;         sc[st] = c; }
.LBB0_85:
	s_or_b64 exec, exec, s[28:29]
	s_and_b64 vcc, exec, s[6:7]
	s_cbranch_vccnz .LBB0_158
	s_cmp_eq_u32 s25, 0
	s_cbranch_scc1 .Lp0_join_1
	v_ashrrev_i32_e32 v79, 31, v78
	v_lshl_add_u64 v[16:17], v[78:79], 2, s[14:15]
	global_load_dwordx2 v[16:17], v[16:17], off offset:32
	s_cmp_gt_i32 s25, 1
	s_mov_b64 s[28:29], -1
	s_cbranch_scc0 .LBB0_88

; DI void tr_item(const TrSrc& s, bf16* WT, int dK, int n0, int k0, LAS unsigned* T, int lane) {
;     ...
;     for (int st = 0; st < 8; ++st) { const int k = k0 + 8 * st + 2 * kq;
; #pragma unroll
;         for (int j = 0; j < 2; ++j) v[st][j] = (nok && k + j < s.kvalid) ? __builtin_nontemporal_load((const f32x4*)(s.p + (size_t)(k + j) * s.ld + s.col0 + 4 * ng)) : (f32x4){0.f, 0.f, 0.f, 0.f};
;         f32x2 c = {1.f, 1.f};
;         if (s.ksc) c = *(const f32x2*)(s.ksc + k);
;         if (s.mumode == 1) { const f32x2 m = *(const f32x2*)(s.mu + k); c = c * (1.0f - m); } else if (s.mumode == 2) { const f32x2 m = *(const f32x2*)(s.mu + k); c = c * m; }
;         sc[st] = c; }
.LBB0_91:
	s_waitcnt vmcnt(0)
	v_mov_b64_e32 v[84:85], v[16:17]
.LBB0_92:
	s_waitcnt vmcnt(0)
.Lp0_join_1:
	v_cmp_gt_i32_e32 vcc, s44, v78
	s_and_b64 s[58:59], s[4:5], vcc
	v_mov_b32_e32 v16, 0
	v_mov_b32_e32 v20, 0
	v_mov_b32_e32 v21, 0
	v_mov_b32_e32 v22, 0
	v_mov_b32_e32 v23, 0
	s_and_saveexec_b64 s[28:29], s[58:59]
	s_cbranch_execz .LBB0_94
	v_add_u32_e32 v17, 16, v78
	v_ashrrev_i32_e32 v18, 31, v17
	v_mul_lo_u32 v20, s26, v18
	v_mul_lo_u32 v21, s27, v17
	v_mad_u64_u32 v[18:19], s[58:59], s26, v17, 0
	v_add3_u32 v19, v19, v20, v21
	v_lshl_add_u64 v[18:19], v[18:19], 2, v[80:81]
	global_load_dwordx4 v[20:23], v[18:19], off nt

; DI void tr_item(const TrSrc& s, bf16* WT, int dK, int n0, int k0, LAS unsigned* T, int lane) {
;     ...
;     for (int st = 0; st < 8; ++st) { const int k = k0 + 8 * st + 2 * kq;
; #pragma unroll
;         for (int j = 0; j < 2; ++j) v[st][j] = (nok && k + j < s.kvalid) ? __builtin_nontemporal_load((const f32x4*)(s.p + (size_t)(k + j) * s.ld + s.col0 + 4 * ng)) : (f32x4){0.f, 0.f, 0.f, 0.f};
;         f32x2 c = {1.f, 1.f};
;         if (s.ksc) c = *(const f32x2*)(s.ksc + k);
;         if (s.mumode == 1) { const f32x2 m = *(const f32x2*)(s.mu + k); c = c * (1.0f - m); } else if (s.mumode == 2) { const f32x2 m = *(const f32x2*)(s.mu + k); c = c * m; }
;         sc[st] = c; }
.LBB0_96:
	s_or_b64 exec, exec, s[28:29]
	s_and_b64 vcc, exec, s[6:7]
	s_cbranch_vccnz .LBB0_159
	s_cmp_eq_u32 s25, 0
	s_cbranch_scc1 .Lp0_join_2
	v_ashrrev_i32_e32 v79, 31, v78
	v_lshl_add_u64 v[24:25], v[78:79], 2, s[14:15]
	global_load_dwordx2 v[24:25], v[24:25], off offset:64
	s_cmp_gt_i32 s25, 1
	s_mov_b64 s[28:29], -1
	s_cbranch_scc0 .LBB0_99

; DI void tr_item(const TrSrc& s, bf16* WT, int dK, int n0, int k0, LAS unsigned* T, int lane) {
;     ...
;     for (int st = 0; st < 8; ++st) { const int k = k0 + 8 * st + 2 * kq;
; #pragma unroll
;         for (int j = 0; j < 2; ++j) v[st][j] = (nok && k + j < s.kvalid) ? __builtin_nontemporal_load((const f32x4*)(s.p + (size_t)(k + j) * s.ld + s.col0 + 4 * ng)) : (f32x4){0.f, 0.f, 0.f, 0.f};
;         f32x2 c = {1.f, 1.f};
;         if (s.ksc) c = *(const f32x2*)(s.ksc + k);
;         if (s.mumode == 1) { const f32x2 m = *(const f32x2*)(s.mu + k); c = c * (1.0f - m); } else if (s.mumode == 2) { const f32x2 m = *(const f32x2*)(s.mu + k); c = c * m; }
;         sc[st] = c; }
.LBB0_102:
	s_waitcnt vmcnt(0)
	v_mov_b64_e32 v[86:87], v[24:25]
.LBB0_103:
	s_waitcnt vmcnt(0)
.Lp0_join_2:
	v_cmp_gt_i32_e32 vcc, s46, v78
	s_and_b64 s[58:59], s[4:5], vcc
	v_mov_b32_e32 v24, 0
	v_mov_b32_e32 v28, 0
	v_mov_b32_e32 v29, 0
	v_mov_b32_e32 v30, 0
	v_mov_b32_e32 v31, 0
	s_and_saveexec_b64 s[28:29], s[58:59]
	s_cbranch_execz .LBB0_105
	v_add_u32_e32 v25, 24, v78
	v_ashrrev_i32_e32 v26, 31, v25
	v_mul_lo_u32 v28, s26, v26
	v_mul_lo_u32 v29, s27, v25
	v_mad_u64_u32 v[26:27], s[58:59], s26, v25, 0
	v_add3_u32 v27, v27, v28, v29
	v_lshl_add_u64 v[26:27], v[26:27], 2, v[80:81]
	global_load_dwordx4 v[28:31], v[26:27], off nt

; DI void tr_item(const TrSrc& s, bf16* WT, int dK, int n0, int k0, LAS unsigned* T, int lane) {
;     ...
;     for (int st = 0; st < 8; ++st) { const int k = k0 + 8 * st + 2 * kq;
; #pragma unroll
;         for (int j = 0; j < 2; ++j) v[st][j] = (nok && k + j < s.kvalid) ? __builtin_nontemporal_load((const f32x4*)(s.p + (size_t)(k + j) * s.ld + s.col0 + 4 * ng)) : (f32x4){0.f, 0.f, 0.f, 0.f};
;         f32x2 c = {1.f, 1.f};
;         if (s.ksc) c = *(const f32x2*)(s.ksc + k);
;         if (s.mumode == 1) { const f32x2 m = *(const f32x2*)(s.mu + k); c = c * (1.0f - m); } else if (s.mumode == 2) { const f32x2 m = *(const f32x2*)(s.mu + k); c = c * m; }
;         sc[st] = c; }
.LBB0_107:
	s_or_b64 exec, exec, s[28:29]
	s_and_b64 vcc, exec, s[6:7]
	s_cbranch_vccnz .LBB0_160
	s_cmp_eq_u32 s25, 0
	s_cbranch_scc1 .Lp0_join_3
	v_ashrrev_i32_e32 v79, 31, v78
	v_lshl_add_u64 v[32:33], v[78:79], 2, s[14:15]
	global_load_dwordx2 v[32:33], v[32:33], off offset:96
	s_cmp_gt_i32 s25, 1
	s_mov_b64 s[28:29], -1
	s_cbranch_scc0 .LBB0_110

; DI void tr_item(const TrSrc& s, bf16* WT, int dK, int n0, int k0, LAS unsigned* T, int lane) {
;     ...
;     for (int st = 0; st < 8; ++st) { const int k = k0 + 8 * st + 2 * kq;
; #pragma unroll
;         for (int j = 0; j < 2; ++j) v[st][j] = (nok && k + j < s.kvalid) ? __builtin_nontemporal_load((const f32x4*)(s.p + (size_t)(k + j) * s.ld + s.col0 + 4 * ng)) : (f32x4){0.f, 0.f, 0.f, 0.f};
;         f32x2 c = {1.f, 1.f};
;         if (s.ksc) c = *(const f32x2*)(s.ksc + k);
;         if (s.mumode == 1) { const f32x2 m = *(const f32x2*)(s.mu + k); c = c * (1.0f - m); } else if (s.mumode == 2) { const f32x2 m = *(const f32x2*)(s.mu + k); c = c * m; }
;         sc[st] = c; }
.LBB0_113:
	s_waitcnt vmcnt(0)
	v_mov_b64_e32 v[88:89], v[32:33]
.LBB0_114:
	s_waitcnt vmcnt(0)
.Lp0_join_3:
	v_cmp_gt_i32_e32 vcc, s48, v78
	s_and_b64 s[58:59], s[4:5], vcc
	v_mov_b32_e32 v32, 0
	v_mov_b32_e32 v36, 0
	v_mov_b32_e32 v37, 0
	v_mov_b32_e32 v38, 0
	v_mov_b32_e32 v39, 0
	s_and_saveexec_b64 s[28:29], s[58:59]
	s_cbranch_execz .LBB0_116
	v_add_u32_e32 v33, 32, v78
	v_ashrrev_i32_e32 v34, 31, v33
	v_mul_lo_u32 v36, s26, v34
	v_mul_lo_u32 v37, s27, v33
	v_mad_u64_u32 v[34:35], s[58:59], s26, v33, 0
	v_add3_u32 v35, v35, v36, v37
	v_lshl_add_u64 v[34:35], v[34:35], 2, v[80:81]
	global_load_dwordx4 v[36:39], v[34:35], off nt

; DI void tr_item(const TrSrc& s, bf16* WT, int dK, int n0, int k0, LAS unsigned* T, int lane) {
;     ...
;     for (int st = 0; st < 8; ++st) { const int k = k0 + 8 * st + 2 * kq;
; #pragma unroll
;         for (int j = 0; j < 2; ++j) v[st][j] = (nok && k + j < s.kvalid) ? __builtin_nontemporal_load((const f32x4*)(s.p + (size_t)(k + j) * s.ld + s.col0 + 4 * ng)) : (f32x4){0.f, 0.f, 0.f, 0.f};
;         f32x2 c = {1.f, 1.f};
;         if (s.ksc) c = *(const f32x2*)(s.ksc + k);
;         if (s.mumode == 1) { const f32x2 m = *(const f32x2*)(s.mu + k); c = c * (1.0f - m); } else if (s.mumode == 2) { const f32x2 m = *(const f32x2*)(s.mu + k); c = c * m; }
;         sc[st] = c; }
.LBB0_118:
	s_or_b64 exec, exec, s[28:29]
	s_and_b64 vcc, exec, s[6:7]
	s_cbranch_vccnz .LBB0_161
	s_cmp_eq_u32 s25, 0
	s_cbranch_scc1 .Lp0_join_4
	v_ashrrev_i32_e32 v79, 31, v78
	v_lshl_add_u64 v[40:41], v[78:79], 2, s[14:15]
	global_load_dwordx2 v[40:41], v[40:41], off offset:128
	s_cmp_gt_i32 s25, 1
	s_mov_b64 s[28:29], -1
	s_cbranch_scc0 .LBB0_121

; DI void tr_item(const TrSrc& s, bf16* WT, int dK, int n0, int k0, LAS unsigned* T, int lane) {
;     ...
;     for (int st = 0; st < 8; ++st) { const int k = k0 + 8 * st + 2 * kq;
; #pragma unroll
;         for (int j = 0; j < 2; ++j) v[st][j] = (nok && k + j < s.kvalid) ? __builtin_nontemporal_load((const f32x4*)(s.p + (size_t)(k + j) * s.ld + s.col0 + 4 * ng)) : (f32x4){0.f, 0.f, 0.f, 0.f};
;         f32x2 c = {1.f, 1.f};
;         if (s.ksc) c = *(const f32x2*)(s.ksc + k);
;         if (s.mumode == 1) { const f32x2 m = *(const f32x2*)(s.mu + k); c = c * (1.0f - m); } else if (s.mumode == 2) { const f32x2 m = *(const f32x2*)(s.mu + k); c = c * m; }
;         sc[st] = c; }
.LBB0_124:
	s_waitcnt vmcnt(0)
	v_mov_b64_e32 v[90:91], v[40:41]
.LBB0_125:
	s_waitcnt vmcnt(0)
.Lp0_join_4:
	v_cmp_gt_i32_e32 vcc, s50, v78
	s_and_b64 s[58:59], s[4:5], vcc
	v_mov_b32_e32 v40, 0
	v_mov_b32_e32 v44, 0
	v_mov_b32_e32 v45, 0
	v_mov_b32_e32 v46, 0
	v_mov_b32_e32 v47, 0
	s_and_saveexec_b64 s[28:29], s[58:59]
	s_cbranch_execz .LBB0_127
	v_add_u32_e32 v41, 40, v78
	v_ashrrev_i32_e32 v42, 31, v41
	v_mul_lo_u32 v44, s26, v42
	v_mul_lo_u32 v45, s27, v41
	v_mad_u64_u32 v[42:43], s[58:59], s26, v41, 0
	v_add3_u32 v43, v43, v44, v45
	v_lshl_add_u64 v[42:43], v[42:43], 2, v[80:81]
	global_load_dwordx4 v[44:47], v[42:43], off nt

; DI void tr_item(const TrSrc& s, bf16* WT, int dK, int n0, int k0, LAS unsigned* T, int lane) {
;     ...
;     for (int st = 0; st < 8; ++st) { const int k = k0 + 8 * st + 2 * kq;
; #pragma unroll
;         for (int j = 0; j < 2; ++j) v[st][j] = (nok && k + j < s.kvalid) ? __builtin_nontemporal_load((const f32x4*)(s.p + (size_t)(k + j) * s.ld + s.col0 + 4 * ng)) : (f32x4){0.f, 0.f, 0.f, 0.f};
;         f32x2 c = {1.f, 1.f};
;         if (s.ksc) c = *(const f32x2*)(s.ksc + k);
;         if (s.mumode == 1) { const f32x2 m = *(const f32x2*)(s.mu + k); c = c * (1.0f - m); } else if (s.mumode == 2) { const f32x2 m = *(const f32x2*)(s.mu + k); c = c * m; }
;         sc[st] = c; }
.LBB0_129:
	s_or_b64 exec, exec, s[28:29]
	s_and_b64 vcc, exec, s[6:7]
	s_cbranch_vccnz .LBB0_162
	s_cmp_eq_u32 s25, 0
	s_cbranch_scc1 .Lp0_join_5
	v_ashrrev_i32_e32 v79, 31, v78
	v_lshl_add_u64 v[48:49], v[78:79], 2, s[14:15]
	global_load_dwordx2 v[48:49], v[48:49], off offset:160
	s_cmp_gt_i32 s25, 1
	s_mov_b64 s[28:29], -1
	s_cbranch_scc0 .LBB0_132

; DI void tr_item(const TrSrc& s, bf16* WT, int dK, int n0, int k0, LAS unsigned* T, int lane) {
;     ...
;     for (int st = 0; st < 8; ++st) { const int k = k0 + 8 * st + 2 * kq;
; #pragma unroll
;         for (int j = 0; j < 2; ++j) v[st][j] = (nok && k + j < s.kvalid) ? __builtin_nontemporal_load((const f32x4*)(s.p + (size_t)(k + j) * s.ld + s.col0 + 4 * ng)) : (f32x4){0.f, 0.f, 0.f, 0.f};
;         f32x2 c = {1.f, 1.f};
;         if (s.ksc) c = *(const f32x2*)(s.ksc + k);
;         if (s.mumode == 1) { const f32x2 m = *(const f32x2*)(s.mu + k); c = c * (1.0f - m); } else if (s.mumode == 2) { const f32x2 m = *(const f32x2*)(s.mu + k); c = c * m; }
;         sc[st] = c; }
.LBB0_135:
	s_waitcnt vmcnt(0)
	v_mov_b64_e32 v[92:93], v[48:49]
.LBB0_136:
	s_waitcnt vmcnt(0)
.Lp0_join_5:
	v_cmp_gt_i32_e32 vcc, s52, v78
	s_and_b64 s[58:59], s[4:5], vcc
	v_mov_b32_e32 v48, 0
	v_mov_b32_e32 v52, 0
	v_mov_b32_e32 v53, 0
	v_mov_b32_e32 v54, 0
	v_mov_b32_e32 v55, 0
	s_and_saveexec_b64 s[28:29], s[58:59]
	s_cbranch_execz .LBB0_138
	v_add_u32_e32 v49, 48, v78
	v_ashrrev_i32_e32 v50, 31, v49
	v_mul_lo_u32 v52, s26, v50
	v_mul_lo_u32 v53, s27, v49
	v_mad_u64_u32 v[50:51], s[58:59], s26, v49, 0
	v_add3_u32 v51, v51, v52, v53
	v_lshl_add_u64 v[50:51], v[50:51], 2, v[80:81]
	global_load_dwordx4 v[52:55], v[50:51], off nt

; DI void tr_item(const TrSrc& s, bf16* WT, int dK, int n0, int k0, LAS unsigned* T, int lane) {
;     ...
;     for (int st = 0; st < 8; ++st) { const int k = k0 + 8 * st + 2 * kq;
; #pragma unroll
;         for (int j = 0; j < 2; ++j) v[st][j] = (nok && k + j < s.kvalid) ? __builtin_nontemporal_load((const f32x4*)(s.p + (size_t)(k + j) * s.ld + s.col0 + 4 * ng)) : (f32x4){0.f, 0.f, 0.f, 0.f};
;         f32x2 c = {1.f, 1.f};
;         if (s.ksc) c = *(const f32x2*)(s.ksc + k);
;         if (s.mumode == 1) { const f32x2 m = *(const f32x2*)(s.mu + k); c = c * (1.0f - m); } else if (s.mumode == 2) { const f32x2 m = *(const f32x2*)(s.mu + k); c = c * m; }
;         sc[st] = c; }
.LBB0_140:
	s_or_b64 exec, exec, s[28:29]
	s_and_b64 vcc, exec, s[6:7]
	s_cbranch_vccnz .LBB0_163
	s_cmp_eq_u32 s25, 0
	s_cbranch_scc1 .Lp0_join_6
	v_ashrrev_i32_e32 v79, 31, v78
	v_lshl_add_u64 v[56:57], v[78:79], 2, s[14:15]
	global_load_dwordx2 v[56:57], v[56:57], off offset:192
	s_cmp_gt_i32 s25, 1
	s_mov_b64 s[28:29], -1
	s_cbranch_scc0 .LBB0_143

; DI void tr_item(const TrSrc& s, bf16* WT, int dK, int n0, int k0, LAS unsigned* T, int lane) {
;     ...
;     for (int st = 0; st < 8; ++st) { const int k = k0 + 8 * st + 2 * kq;
; #pragma unroll
;         for (int j = 0; j < 2; ++j) v[st][j] = (nok && k + j < s.kvalid) ? __builtin_nontemporal_load((const f32x4*)(s.p + (size_t)(k + j) * s.ld + s.col0 + 4 * ng)) : (f32x4){0.f, 0.f, 0.f, 0.f};
;         f32x2 c = {1.f, 1.f};
;         if (s.ksc) c = *(const f32x2*)(s.ksc + k);
;         if (s.mumode == 1) { const f32x2 m = *(const f32x2*)(s.mu + k); c = c * (1.0f - m); } else if (s.mumode == 2) { const f32x2 m = *(const f32x2*)(s.mu + k); c = c * m; }
;         sc[st] = c; }
.LBB0_146:
	s_waitcnt vmcnt(0)
	v_mov_b64_e32 v[94:95], v[56:57]
.LBB0_147:
	s_waitcnt vmcnt(0)
.Lp0_join_6:
	v_cmp_gt_i32_e32 vcc, s54, v78
	s_and_b64 s[58:59], s[4:5], vcc
	v_mov_b32_e32 v56, 0
	v_mov_b32_e32 v60, 0
	v_mov_b32_e32 v61, 0
	v_mov_b32_e32 v62, 0
	v_mov_b32_e32 v63, 0
	s_and_saveexec_b64 s[28:29], s[58:59]
	s_cbranch_execz .LBB0_149
	v_add_u32_e32 v57, 56, v78
	v_ashrrev_i32_e32 v58, 31, v57
	v_mul_lo_u32 v60, s26, v58
	v_mul_lo_u32 v61, s27, v57
	v_mad_u64_u32 v[58:59], s[58:59], s26, v57, 0
	v_add3_u32 v59, v59, v60, v61
	v_lshl_add_u64 v[58:59], v[58:59], 2, v[80:81]
	global_load_dwordx4 v[60:63], v[58:59], off nt
